# v037 + GDN scan: 7 packed v_pk_mul_f32 feeding MFMA accumulators split into scalar v_mul pairs (bit-identical)
# speedup vs baseline: 1.0096x; 1.0031x over previous
.LBB0_3681:
	s_nop 1
	v_mul_f32_e32 v57, 0x3fb8aa3b, v66
	v_exp_f32_e32 v104, v57
	v_mul_f32_e32 v57, 0x3fb8aa3b, v67
	v_exp_f32_e32 v105, v57
	v_mul_f32_e32 v57, 0x3fb8aa3b, v68
	v_mul_f32_e32 v56, 0x3fb8aa3b, v143
	v_exp_f32_e32 v106, v57
	v_mul_f32_e32 v57, 0x3fb8aa3b, v69
	v_exp_f32_e32 v107, v57
	v_exp_f32_e32 v80, v56
	s_waitcnt lgkmcnt(0)
	s_barrier
	ds_read_b128 v[56:59], v129 offset:55296
	ds_read_b128 v[70:73], v135 offset:36864
	ds_read_b128 v[66:69], v129 offset:64512
	ds_read_b128 v[100:103], v135 offset:46080
	ds_read_b128 v[216:219], v65 offset:36864
	ds_read_b128 v[222:225], v65 offset:46080
	ds_read_b128 v[226:229], v129 offset:55360
	ds_read_b128 v[234:237], v135 offset:36928
	ds_read_b128 v[242:245], v65 offset:36928
	ds_read_b128 v[230:233], v129 offset:64576
	ds_read_b128 v[238:241], v135 offset:46144
	ds_read_b128 v[246:249], v65 offset:46144
	v_mul_f32_e32 v46, v46, v106
	v_mul_f32_e32 v47, v47, v107
	v_mul_f32_e32 v44, v44, v104
	v_mul_f32_e32 v45, v45, v105
	v_mul_f32_e32 v50, v50, v80
	v_mul_f32_e32 v51, v51, v80
	v_mul_f32_e32 v48, v48, v80
	v_mul_f32_e32 v49, v49, v80
	s_waitcnt lgkmcnt(10)
	v_mfma_f32_16x16x32_bf16 v[44:47], v[56:59], v[70:73], v[44:47]
	v_mul_f32_e64 v62, v62, v106
	v_mul_f32_e64 v63, v63, v107
	v_mul_f32_e32 v60, v60, v104
	v_mul_f32_e32 v61, v61, v105
	v_mul_f32_e32 v54, v54, v80
	v_mul_f32_e32 v55, v55, v80
	s_waitcnt lgkmcnt(8)
	v_mfma_f32_16x16x32_bf16 v[48:51], v[66:69], v[100:103], v[48:51]
	v_mul_f32_e32 v52, v52, v80
	v_mul_f32_e32 v53, v53, v80
	v_add_u32_e32 v147, v117, v119
	s_waitcnt lgkmcnt(7)
	v_mfma_f32_16x16x32_bf16 v[56:59], v[56:59], v[216:219], v[60:63]
	v_add_u32_e32 v148, v117, v121
	s_waitcnt lgkmcnt(6)
	v_mfma_f32_16x16x32_bf16 v[52:55], v[66:69], v[222:225], v[52:55]
	s_waitcnt lgkmcnt(4)
	v_mfma_f32_16x16x32_bf16 v[44:47], v[226:229], v[234:237], v[44:47]
	s_waitcnt lgkmcnt(3)
	v_mfma_f32_16x16x32_bf16 v[56:59], v[226:229], v[242:245], v[56:59]
	s_waitcnt lgkmcnt(1)
	v_mfma_f32_16x16x32_bf16 v[48:51], v[230:233], v[238:241], v[48:51]
	s_waitcnt lgkmcnt(0)
	v_mfma_f32_16x16x32_bf16 v[52:55], v[230:233], v[246:249], v[52:55]
	s_nop 1
	ds_write2_b32 v133, v44, v45 offset1:68
	ds_write2_b32 v133, v46, v47 offset0:136 offset1:204
	s_nop 5
	v_cvt_pk_bf16_f32 v44, v48, v49
	v_cvt_pk_bf16_f32 v45, v50, v51
	ds_write_b64 v147, v[44:45] offset:27648
	ds_write2_b32 v134, v56, v57 offset1:68
	ds_write2_b32 v134, v58, v59 offset0:136 offset1:204
	v_cvt_pk_bf16_f32 v44, v52, v53
	v_cvt_pk_bf16_f32 v45, v54, v55
	ds_write_b64 v148, v[44:45] offset:27648
	s_cmp_eq_u32 s101, 0
	s_cbranch_scc1 .Lg_noD1
	s_and_b64 vcc, exec, s[8:9]
	s_cbranch_vccz .Lg_w0
	s_waitcnt vmcnt(14)
	s_branch .Lg_w1
